# filter GEMM loop: hi/lo bf16 operand split and bf16 output via v_cvt_pk_bf16_f32 instead of integer RNE bit trick (VALU-bound loop, 323 -> 126 instrs)
# speedup vs baseline: 1.0040x; 1.0040x over previous
.LBB0_324:
	s_waitcnt lgkmcnt(6)
	v_cvt_pk_bf16_f32 v116, v94, v95
	v_cvt_pk_bf16_f32 v117, v96, v97
	v_cvt_pk_bf16_f32 v118, v90, v91
	v_cvt_pk_bf16_f32 v119, v92, v93
	v_lshlrev_b32_e32 v128, 16, v116
	v_and_b32_e32 v129, s1, v116
	v_pk_add_f32 v[94:95], v[94:95], v[128:129] neg_lo:[0,1] neg_hi:[0,1]
	v_lshlrev_b32_e32 v130, 16, v117
	v_and_b32_e32 v131, s1, v117
	v_pk_add_f32 v[96:97], v[96:97], v[130:131] neg_lo:[0,1] neg_hi:[0,1]
	v_lshlrev_b32_e32 v128, 16, v118
	v_and_b32_e32 v129, s1, v118
	v_pk_add_f32 v[90:91], v[90:91], v[128:129] neg_lo:[0,1] neg_hi:[0,1]
	v_lshlrev_b32_e32 v130, 16, v119
	v_and_b32_e32 v131, s1, v119
	v_pk_add_f32 v[92:93], v[92:93], v[130:131] neg_lo:[0,1] neg_hi:[0,1]
	v_cvt_pk_bf16_f32 v120, v94, v95
	v_cvt_pk_bf16_f32 v121, v96, v97
	v_cvt_pk_bf16_f32 v122, v90, v91
	v_cvt_pk_bf16_f32 v123, v92, v93
	s_waitcnt lgkmcnt(4)
	v_cvt_pk_bf16_f32 v88, v12, v13
	v_cvt_pk_bf16_f32 v89, v14, v15
	v_cvt_pk_bf16_f32 v90, v8, v9
	v_cvt_pk_bf16_f32 v91, v10, v11
	v_lshlrev_b32_e32 v128, 16, v88
	v_and_b32_e32 v129, s1, v88
	v_pk_add_f32 v[12:13], v[12:13], v[128:129] neg_lo:[0,1] neg_hi:[0,1]
	v_lshlrev_b32_e32 v130, 16, v89
	v_and_b32_e32 v131, s1, v89
	v_pk_add_f32 v[14:15], v[14:15], v[130:131] neg_lo:[0,1] neg_hi:[0,1]
	v_lshlrev_b32_e32 v128, 16, v90
	v_and_b32_e32 v129, s1, v90
	v_pk_add_f32 v[8:9], v[8:9], v[128:129] neg_lo:[0,1] neg_hi:[0,1]
	v_lshlrev_b32_e32 v130, 16, v91
	v_and_b32_e32 v131, s1, v91
	v_pk_add_f32 v[10:11], v[10:11], v[130:131] neg_lo:[0,1] neg_hi:[0,1]
	v_cvt_pk_bf16_f32 v92, v12, v13
	v_cvt_pk_bf16_f32 v93, v14, v15
	v_cvt_pk_bf16_f32 v94, v8, v9
	v_cvt_pk_bf16_f32 v95, v10, v11
	s_waitcnt lgkmcnt(2)
	v_cvt_pk_bf16_f32 v96, v4, v5
	v_cvt_pk_bf16_f32 v97, v6, v7
	v_cvt_pk_bf16_f32 v98, v0, v1
	v_cvt_pk_bf16_f32 v99, v2, v3
	v_lshlrev_b32_e32 v128, 16, v96
	v_and_b32_e32 v129, s1, v96
	v_pk_add_f32 v[4:5], v[4:5], v[128:129] neg_lo:[0,1] neg_hi:[0,1]
	v_lshlrev_b32_e32 v130, 16, v97
	v_and_b32_e32 v131, s1, v97
	v_pk_add_f32 v[6:7], v[6:7], v[130:131] neg_lo:[0,1] neg_hi:[0,1]
	v_lshlrev_b32_e32 v128, 16, v98
	v_and_b32_e32 v129, s1, v98
	v_pk_add_f32 v[0:1], v[0:1], v[128:129] neg_lo:[0,1] neg_hi:[0,1]
	v_lshlrev_b32_e32 v130, 16, v99
	v_and_b32_e32 v131, s1, v99
	v_pk_add_f32 v[2:3], v[2:3], v[130:131] neg_lo:[0,1] neg_hi:[0,1]
	v_cvt_pk_bf16_f32 v132, v4, v5
	v_cvt_pk_bf16_f32 v133, v6, v7
	v_cvt_pk_bf16_f32 v134, v0, v1
	v_cvt_pk_bf16_f32 v135, v2, v3
	s_nop 1
	v_mfma_f32_32x32x16_bf16 v[0:15], v[72:75], v[116:119], 0
	v_mfma_f32_32x32x16_bf16 v[0:15], v[76:79], v[120:123], v[0:15]
	v_mfma_f32_32x32x16_bf16 v[0:15], v[76:79], v[116:119], v[0:15]
	s_waitcnt lgkmcnt(0)
	v_cvt_pk_bf16_f32 v124, v84, v85
	v_cvt_pk_bf16_f32 v125, v86, v87
	v_cvt_pk_bf16_f32 v126, v80, v81
	v_cvt_pk_bf16_f32 v127, v82, v83
	v_lshlrev_b32_e32 v128, 16, v124
	v_and_b32_e32 v129, s1, v124
	v_pk_add_f32 v[84:85], v[84:85], v[128:129] neg_lo:[0,1] neg_hi:[0,1]
	v_lshlrev_b32_e32 v130, 16, v125
	v_and_b32_e32 v131, s1, v125
	v_pk_add_f32 v[86:87], v[86:87], v[130:131] neg_lo:[0,1] neg_hi:[0,1]
	v_lshlrev_b32_e32 v128, 16, v126
	v_and_b32_e32 v129, s1, v126
	v_pk_add_f32 v[80:81], v[80:81], v[128:129] neg_lo:[0,1] neg_hi:[0,1]
	v_lshlrev_b32_e32 v130, 16, v127
	v_and_b32_e32 v131, s1, v127
	v_pk_add_f32 v[82:83], v[82:83], v[130:131] neg_lo:[0,1] neg_hi:[0,1]
	v_cvt_pk_bf16_f32 v84, v84, v85
	v_cvt_pk_bf16_f32 v85, v86, v87
	v_cvt_pk_bf16_f32 v86, v80, v81
	v_cvt_pk_bf16_f32 v87, v82, v83
	v_mfma_f32_32x32x16_bf16 v[0:15], v[32:35], v[88:91], v[0:15]
	v_mfma_f32_32x32x16_bf16 v[0:15], v[36:39], v[92:95], v[0:15]
	v_mfma_f32_32x32x16_bf16 v[0:15], v[36:39], v[88:91], v[0:15]
	v_mfma_f32_32x32x16_bf16 v[0:15], v[24:27], v[96:99], v[0:15]
	v_mfma_f32_32x32x16_bf16 v[0:15], v[28:31], v[132:135], v[0:15]
	v_mfma_f32_32x32x16_bf16 v[0:15], v[28:31], v[96:99], v[0:15]
	s_and_b32 s8, s9, 1
	s_mov_b32 s7, 1
	v_mfma_f32_32x32x16_bf16 v[0:15], v[16:19], v[124:127], v[0:15]
	v_mfma_f32_32x32x16_bf16 v[0:15], v[20:23], v[84:87], v[0:15]
	s_andn2_b64 vcc, exec, s[4:5]
	v_mfma_f32_32x32x16_bf16 v[0:15], v[20:23], v[124:127], v[0:15]
	v_lshl_add_u32 v80, s8, 6, v112
	s_nop 11
	v_cvt_pk_bf16_f32 v128, v0, v1
	ds_write_b16 v80, v128 offset:8704
	ds_write_b16_d16_hi v80, v128 offset:8848
	v_cvt_pk_bf16_f32 v129, v2, v3
	ds_write_b16 v80, v129 offset:8992
	ds_write_b16_d16_hi v80, v129 offset:9136
	v_cvt_pk_bf16_f32 v128, v4, v5
	ds_write_b16 v80, v128 offset:9856
	ds_write_b16_d16_hi v80, v128 offset:10000
	v_cvt_pk_bf16_f32 v129, v6, v7
	ds_write_b16 v80, v129 offset:10144
	ds_write_b16_d16_hi v80, v129 offset:10288
	v_cvt_pk_bf16_f32 v128, v8, v9
	ds_write_b16 v80, v128 offset:11008
	ds_write_b16_d16_hi v80, v128 offset:11152
	v_cvt_pk_bf16_f32 v129, v10, v11
	ds_write_b16 v80, v129 offset:11296
	ds_write_b16_d16_hi v80, v129 offset:11440
	v_cvt_pk_bf16_f32 v128, v12, v13
	ds_write_b16 v80, v128 offset:12160
	ds_write_b16_d16_hi v80, v128 offset:12304
	v_cvt_pk_bf16_f32 v129, v14, v15
	ds_write_b16 v80, v129 offset:12448
	ds_write_b16_d16_hi v80, v129 offset:12592
	s_cbranch_vccnz .LBB0_321
	s_waitcnt lgkmcnt(0)
	s_lshl_b32 s4, s9, 5
	ds_read_b128 v[0:3], v115 offset:8704
	ds_read_b128 v[4:7], v115 offset:9856
	s_andn2_b32 s4, s4, 63
	s_ashr_i32 s5, s4, 31
	s_lshl_b64 s[4:5], s[4:5], 1
	v_lshl_add_u64 v[8:9], v[100:101], 0, s[4:5]
	s_waitcnt lgkmcnt(1)
	global_store_dwordx4 v[8:9], v[0:3], off
	ds_read_b128 v[0:3], v115 offset:11008
	ds_read_b128 v[8:11], v115 offset:12160
	v_lshl_add_u64 v[12:13], v[102:103], 0, s[4:5]
	s_waitcnt lgkmcnt(2)
	global_store_dwordx4 v[12:13], v[4:7], off
	s_mov_b32 s7, s3
	s_nop 0
	v_lshl_add_u64 v[4:5], v[104:105], 0, s[4:5]
	s_waitcnt lgkmcnt(1)
	global_store_dwordx4 v[4:5], v[0:3], off
	s_nop 1
	v_lshl_add_u64 v[0:1], v[106:107], 0, s[4:5]
	s_waitcnt lgkmcnt(0)
	global_store_dwordx4 v[0:1], v[8:11], off
	s_waitcnt lgkmcnt(0)
	s_branch .LBB0_321
